# epifuse=load: P1 SwiGLU batch 0 runs in the last K iteration's load segment (wave otherwise idle at the barrier), temps v226-243
# baseline (speedup 1.0000x reference)
; #define PG8_STAGE(bufoff, gbase, voff) do { _Pragma("unroll") for (int _i = 0; _i < 2; ++_i) \
;         __builtin_amdgcn_global_load_lds((const unsigned*)((const char*)(gbase) + (voff)[_i]), (PG8_LAS unsigned*)(lds + (bufoff) + ldsw + _i * 8192), 16, 0, 0); } while (0)
; #define PG8_LDA(dst, b, h) do { _Pragma("unroll") for (int m = 0; m < 4; ++m) _Pragma("unroll") for (int k = 0; k < 2; ++k) dst[m][k] = *(const PG8_LAS bf16x8*)(lds + PG8_SA(b, h) + aoff + m * 2048 + k * 1024); } while (0)
; #define PG8_LDB(dst, b, h) do { _Pragma("unroll") for (int n = 0; n < 2; ++n) _Pragma("unroll") for (int k = 0; k < 2; ++k) dst[n][k] = *(const PG8_LAS bf16x8*)(lds + PG8_SB(b, h) + boff + n * 2048 + k * 1024); } while (0)
; #define PG8_MMA(ai, bj, At, Bt) do { __builtin_amdgcn_s_setprio(1); _Pragma("unroll") for (int m = 0; m < 4; ++m) _Pragma("unroll") for (int n = 0; n < 2; ++n) _Pragma("unroll") for (int k = 0; k < 2; ++k) \
;         acc[ai][bj][m][n] = __builtin_amdgcn_mfma_f32_16x16x32_bf16(Bt[n][k], At[m][k], acc[ai][bj][m][n], 0, 0, 0); __builtin_amdgcn_s_setprio(0); } while (0)
; #define PG8_WAIT_V(n) asm volatile("s_waitcnt vmcnt(" #n ")" ::: "memory")
; #define PG8_WAIT_L(n) asm volatile("s_waitcnt lgkmcnt(" #n ")" ::: "memory")
; #define PG8_BAR __builtin_amdgcn_s_barrier()
; #define PG8_SCHED __builtin_amdgcn_sched_barrier(0)
; template <class Epi, class Sched, bool ALIGN_EPI = false, bool SP2 = false>
; __device__ __forceinline__ void gemm_phase(PG8_LAS unsigned char* lds, const Gemm g, const Sched& S, const Epi& E) {
;     ...
;             PG8_WAIT_V(8); PG8_WAIT_L(0); PG8_BAR; PG8_MMA(1, 0, At, B0); PG8_MMA(1, 1, At, B1); PG8_BAR; PG8_SCHED;
;             PG8_LDB(B0, 1, 0); PG8_LDB(B1, 1, 1); PG8_SCHED; PG8_LDA(At, 1, 0); PG8_STAGE(PG8_SA(0, 1), a2 + hstep, voffA);
;             PG8_WAIT_V(8); PG8_WAIT_L(0); PG8_BAR; PG8_MMA(0, 0, At, B0); PG8_MMA(0, 1, At, B1); PG8_BAR; PG8_SCHED;
;             PG8_LDA(At, 1, 1); PG8_STAGE(PG8_SB(1, 0), b3, voffB); PG8_STAGE(PG8_SB(1, 1), b3 + hstep, voffB); PG8_STAGE(PG8_SA(1, 0), a3, voffA);
.Lrw0_b1:
	s_waitcnt lgkmcnt(0)
	s_barrier
	s_setprio 1
	s_waitcnt lgkmcnt(0)
	v_mfma_f32_16x16x32_bf16 v[60:63], v[144:147], v[182:185], v[60:63]
	v_mfma_f32_16x16x32_bf16 v[56:59], v[158:161], v[182:185], v[56:59]
	v_mfma_f32_16x16x32_bf16 v[44:47], v[144:147], v[190:193], v[44:47]
	v_mfma_f32_16x16x32_bf16 v[40:43], v[158:161], v[190:193], v[40:43]
	v_mfma_f32_16x16x32_bf16 v[28:31], v[144:147], v[202:205], v[28:31]
	v_mfma_f32_16x16x32_bf16 v[24:27], v[158:161], v[202:205], v[24:27]
	v_mfma_f32_16x16x32_bf16 v[12:15], v[144:147], v[210:213], v[12:15]
	v_mfma_f32_16x16x32_bf16 v[8:11], v[158:161], v[210:213], v[8:11]
	v_mfma_f32_16x16x32_bf16 v[60:63], v[154:157], v[186:189], v[60:63]
	v_mfma_f32_16x16x32_bf16 v[56:59], v[162:165], v[186:189], v[56:59]
	v_mfma_f32_16x16x32_bf16 v[44:47], v[154:157], v[198:201], v[44:47]
	v_mfma_f32_16x16x32_bf16 v[40:43], v[162:165], v[198:201], v[40:43]
	v_mfma_f32_16x16x32_bf16 v[28:31], v[154:157], v[206:209], v[28:31]
	v_mfma_f32_16x16x32_bf16 v[24:27], v[162:165], v[206:209], v[24:27]
	v_mfma_f32_16x16x32_bf16 v[12:15], v[154:157], v[214:217], v[12:15]
	v_mfma_f32_16x16x32_bf16 v[8:11], v[162:165], v[214:217], v[8:11]
	s_setprio 0
	s_setprio 1
	v_mfma_f32_16x16x32_bf16 v[52:55], v[166:169], v[182:185], v[52:55]
	v_mfma_f32_16x16x32_bf16 v[48:51], v[174:177], v[182:185], v[48:51]
	v_mfma_f32_16x16x32_bf16 v[36:39], v[166:169], v[190:193], v[36:39]
	v_mfma_f32_16x16x32_bf16 v[32:35], v[174:177], v[190:193], v[32:35]
	v_mfma_f32_16x16x32_bf16 v[20:23], v[166:169], v[202:205], v[20:23]
	v_mfma_f32_16x16x32_bf16 v[16:19], v[174:177], v[202:205], v[16:19]
	v_mfma_f32_16x16x32_bf16 v[4:7], v[166:169], v[210:213], v[4:7]
	v_mfma_f32_16x16x32_bf16 v[0:3], v[174:177], v[210:213], v[0:3]
	v_mfma_f32_16x16x32_bf16 v[52:55], v[170:173], v[186:189], v[52:55]
	v_mfma_f32_16x16x32_bf16 v[48:51], v[178:181], v[186:189], v[48:51]
	v_mfma_f32_16x16x32_bf16 v[36:39], v[170:173], v[198:201], v[36:39]
	v_mfma_f32_16x16x32_bf16 v[32:35], v[178:181], v[198:201], v[32:35]
	v_mfma_f32_16x16x32_bf16 v[20:23], v[170:173], v[206:209], v[20:23]
	v_mfma_f32_16x16x32_bf16 v[16:19], v[178:181], v[206:209], v[16:19]
	v_mfma_f32_16x16x32_bf16 v[4:7], v[170:173], v[214:217], v[4:7]
	v_mfma_f32_16x16x32_bf16 v[0:3], v[178:181], v[214:217], v[0:3]
	s_setprio 0
	s_barrier
	s_add_i32 s51, 0, 0x18000
	s_add_i32 s52, 0, 0x1c000
	v_add_u32_e32 v162, s51, v149
	v_add_u32_e32 v178, s52, v149
	ds_read_b128 v[144:147], v162
	ds_read_b128 v[154:157], v162 offset:1024
	ds_read_b128 v[158:161], v162 offset:2048
	ds_read_b128 v[162:165], v162 offset:3072
	ds_read_b128 v[166:169], v178
	ds_read_b128 v[170:173], v178 offset:1024
	ds_read_b128 v[174:177], v178 offset:2048
	ds_read_b128 v[178:181], v178 offset:3072
	s_add_u32 s28, s28, 0x40000
	s_addc_u32 s29, s29, 0
	s_mov_b32 m0, s35
	v_lshl_add_u64 v[224:225], s[28:29], 0, v[128:129]
	ds_read_b128 v[182:185], v153 offset:32768
	ds_read_b128 v[186:189], v153 offset:33792
	ds_read_b128 v[190:193], v153 offset:34816
	ds_read_b128 v[198:201], v153 offset:35840
	ds_read_b128 v[202:205], v153 offset:36864
	ds_read_b128 v[206:209], v153 offset:37888
	ds_read_b128 v[210:213], v153 offset:38912
	ds_read_b128 v[214:217], v153 offset:39936
	global_load_lds_dwordx4 v[224:225], off
	v_lshl_add_u64 v[224:225], s[28:29], 0, v[132:133]
	s_mov_b32 m0, s36
	s_nop 0
	global_load_lds_dwordx4 v[224:225], off
	s_waitcnt vmcnt(8)
	s_waitcnt lgkmcnt(0)
	s_barrier
	s_setprio 1
	s_waitcnt lgkmcnt(0)
	v_mfma_f32_16x16x32_bf16 v[124:127], v[144:147], v[182:185], v[124:127]
	v_mfma_f32_16x16x32_bf16 v[120:123], v[158:161], v[182:185], v[120:123]
	v_mfma_f32_16x16x32_bf16 v[108:111], v[144:147], v[190:193], v[108:111]
	v_mfma_f32_16x16x32_bf16 v[104:107], v[158:161], v[190:193], v[104:107]
	v_mfma_f32_16x16x32_bf16 v[92:95], v[144:147], v[202:205], v[92:95]
	v_mfma_f32_16x16x32_bf16 v[88:91], v[158:161], v[202:205], v[88:91]
	v_mfma_f32_16x16x32_bf16 v[76:79], v[144:147], v[210:213], v[76:79]
	v_mfma_f32_16x16x32_bf16 v[72:75], v[158:161], v[210:213], v[72:75]
	v_mfma_f32_16x16x32_bf16 v[124:127], v[154:157], v[186:189], v[124:127]
	v_mfma_f32_16x16x32_bf16 v[120:123], v[162:165], v[186:189], v[120:123]
	v_mfma_f32_16x16x32_bf16 v[108:111], v[154:157], v[198:201], v[108:111]
	v_mfma_f32_16x16x32_bf16 v[104:107], v[162:165], v[198:201], v[104:107]
	v_mfma_f32_16x16x32_bf16 v[92:95], v[154:157], v[206:209], v[92:95]
	v_mfma_f32_16x16x32_bf16 v[88:91], v[162:165], v[206:209], v[88:91]
	v_mfma_f32_16x16x32_bf16 v[76:79], v[154:157], v[214:217], v[76:79]
	v_mfma_f32_16x16x32_bf16 v[72:75], v[162:165], v[214:217], v[72:75]
	s_setprio 0
	s_setprio 1
	v_mfma_f32_16x16x32_bf16 v[116:119], v[166:169], v[182:185], v[116:119]
	v_mfma_f32_16x16x32_bf16 v[112:115], v[174:177], v[182:185], v[112:115]
	v_mfma_f32_16x16x32_bf16 v[100:103], v[166:169], v[190:193], v[100:103]
	v_mfma_f32_16x16x32_bf16 v[96:99], v[174:177], v[190:193], v[96:99]
	v_mfma_f32_16x16x32_bf16 v[84:87], v[166:169], v[202:205], v[84:87]
	v_mfma_f32_16x16x32_bf16 v[80:83], v[174:177], v[202:205], v[80:83]
	v_mfma_f32_16x16x32_bf16 v[68:71], v[166:169], v[210:213], v[68:71]
	v_mfma_f32_16x16x32_bf16 v[64:67], v[174:177], v[210:213], v[64:67]
	v_mfma_f32_16x16x32_bf16 v[116:119], v[170:173], v[186:189], v[116:119]
	v_mfma_f32_16x16x32_bf16 v[112:115], v[178:181], v[186:189], v[112:115]
	v_mfma_f32_16x16x32_bf16 v[100:103], v[170:173], v[198:201], v[100:103]
	v_mfma_f32_16x16x32_bf16 v[96:99], v[178:181], v[198:201], v[96:99]
	v_mfma_f32_16x16x32_bf16 v[84:87], v[170:173], v[206:209], v[84:87]
	v_mfma_f32_16x16x32_bf16 v[80:83], v[178:181], v[206:209], v[80:83]
	v_mfma_f32_16x16x32_bf16 v[68:71], v[170:173], v[214:217], v[68:71]
	v_mfma_f32_16x16x32_bf16 v[64:67], v[178:181], v[214:217], v[64:67]
	s_setprio 0
	s_barrier
	s_add_i32 s28, s51, s30
	v_lshl_add_u64 v[194:195], v[194:195], 0, s[10:11]
	s_mov_b32 m0, s28
	ds_read_b128 v[182:185], v153 offset:49152
	ds_read_b128 v[186:189], v153 offset:50176
	ds_read_b128 v[190:193], v153 offset:51200
	ds_read_b128 v[198:201], v153 offset:52224
	ds_read_b128 v[202:205], v153 offset:53248
	ds_read_b128 v[206:209], v153 offset:54272
	ds_read_b128 v[210:213], v153 offset:55296
	ds_read_b128 v[214:217], v153 offset:56320
	global_load_lds_dwordx4 v[194:195], off
	s_add_i32 m0, s28, 0x2000
	s_add_u32 s26, s26, 0x40080
	v_lshl_add_u64 v[194:195], v[218:219], 0, s[10:11]
	s_addc_u32 s27, s27, 0
	s_add_i32 s28, s52, s30
	global_load_lds_dwordx4 v[194:195], off
	v_lshl_add_u64 v[194:195], s[26:27], 0, v[130:131]
	s_mov_b32 m0, s28
	s_nop 0
	global_load_lds_dwordx4 v[194:195], off
	v_lshl_add_u64 v[194:195], s[26:27], 0, v[134:135]
	s_add_i32 m0, s28, 0x2000
	s_nop 0
	global_load_lds_dwordx4 v[194:195], off
	v_lshl_add_u64 v[194:195], v[220:221], 0, s[10:11]
	s_mov_b32 m0, s39
	s_nop 0
	global_load_lds_dwordx4 v[194:195], off
	v_lshl_add_u64 v[194:195], v[222:223], 0, s[10:11]
	s_mov_b32 m0, s40
	s_nop 0
	global_load_lds_dwordx4 v[194:195], off
	s_cmp_eq_u32 s50, 12
	s_cbranch_scc1 .Lfz1_tail
; #define PG8_MMA(ai, bj, At, Bt) do { __builtin_amdgcn_s_setprio(1); _Pragma("unroll") for (int m = 0; m < 4; ++m) _Pragma("unroll") for (int n = 0; n < 2; ++n) _Pragma("unroll") for (int k = 0; k < 2; ++k) \
;         acc[ai][bj][m][n] = __builtin_amdgcn_mfma_f32_16x16x32_bf16(Bt[n][k], At[m][k], acc[ai][bj][m][n], 0, 0, 0); __builtin_amdgcn_s_setprio(0); } while (0)
; #define PG8_WAIT_V(n) asm volatile("s_waitcnt vmcnt(" #n ")" ::: "memory")
; #define PG8_WAIT_L(n) asm volatile("s_waitcnt lgkmcnt(" #n ")" ::: "memory")
; #define PG8_BAR __builtin_amdgcn_s_barrier()
; #define PG8_SCHED __builtin_amdgcn_sched_barrier(0)
; template <class Epi, class Sched, bool ALIGN_EPI = false, bool SP2 = false>
; __device__ __forceinline__ void gemm_phase(PG8_LAS unsigned char* lds, const Gemm g, const Sched& S, const Epi& E) {
;     ...
;         for (int t = 0; t < nt; t += 2) {
;             const bool last = (t == nt - 2);
;             const char* a1 = cA + (size_t)(t + 1) * kstep;
;             const char* a2 = last ? nA : cA + (size_t)(t + 2) * kstep; const char* b2 = last ? nB : cB + (size_t)(t + 2) * kstep;
;     ...
;             PG8_WAIT_V(8); PG8_WAIT_L(0); PG8_BAR; PG8_MMA(1, 0, At, B0); PG8_MMA(1, 1, At, B1); PG8_BAR; PG8_SCHED;
.Lfz1_back:
	s_waitcnt vmcnt(8)
	s_waitcnt lgkmcnt(0)
	s_barrier
	s_setprio 1
	s_waitcnt lgkmcnt(0)
	v_mfma_f32_16x16x32_bf16 v[60:63], v[144:147], v[182:185], v[60:63]
	v_mfma_f32_16x16x32_bf16 v[56:59], v[158:161], v[182:185], v[56:59]
	v_mfma_f32_16x16x32_bf16 v[44:47], v[144:147], v[190:193], v[44:47]
	v_mfma_f32_16x16x32_bf16 v[40:43], v[158:161], v[190:193], v[40:43]
	v_mfma_f32_16x16x32_bf16 v[28:31], v[144:147], v[202:205], v[28:31]
	v_mfma_f32_16x16x32_bf16 v[24:27], v[158:161], v[202:205], v[24:27]
	v_mfma_f32_16x16x32_bf16 v[12:15], v[144:147], v[210:213], v[12:15]
	v_mfma_f32_16x16x32_bf16 v[8:11], v[158:161], v[210:213], v[8:11]
	v_mfma_f32_16x16x32_bf16 v[60:63], v[154:157], v[186:189], v[60:63]
	v_mfma_f32_16x16x32_bf16 v[56:59], v[162:165], v[186:189], v[56:59]
	v_mfma_f32_16x16x32_bf16 v[44:47], v[154:157], v[198:201], v[44:47]
	v_mfma_f32_16x16x32_bf16 v[40:43], v[162:165], v[198:201], v[40:43]
	v_mfma_f32_16x16x32_bf16 v[28:31], v[154:157], v[206:209], v[28:31]
	v_mfma_f32_16x16x32_bf16 v[24:27], v[162:165], v[206:209], v[24:27]
	v_mfma_f32_16x16x32_bf16 v[12:15], v[154:157], v[214:217], v[12:15]
	v_mfma_f32_16x16x32_bf16 v[8:11], v[162:165], v[214:217], v[8:11]
	s_setprio 0
	s_setprio 1
	v_mfma_f32_16x16x32_bf16 v[52:55], v[166:169], v[182:185], v[52:55]
	v_mfma_f32_16x16x32_bf16 v[48:51], v[174:177], v[182:185], v[48:51]
	v_mfma_f32_16x16x32_bf16 v[36:39], v[166:169], v[190:193], v[36:39]
	v_mfma_f32_16x16x32_bf16 v[32:35], v[174:177], v[190:193], v[32:35]
	v_mfma_f32_16x16x32_bf16 v[20:23], v[166:169], v[202:205], v[20:23]
	v_mfma_f32_16x16x32_bf16 v[16:19], v[174:177], v[202:205], v[16:19]
	v_mfma_f32_16x16x32_bf16 v[4:7], v[166:169], v[210:213], v[4:7]
	v_mfma_f32_16x16x32_bf16 v[0:3], v[174:177], v[210:213], v[0:3]
	v_mfma_f32_16x16x32_bf16 v[52:55], v[170:173], v[186:189], v[52:55]
	v_mfma_f32_16x16x32_bf16 v[48:51], v[178:181], v[186:189], v[48:51]
	v_mfma_f32_16x16x32_bf16 v[36:39], v[170:173], v[198:201], v[36:39]
	v_mfma_f32_16x16x32_bf16 v[32:35], v[178:181], v[198:201], v[32:35]
	v_mfma_f32_16x16x32_bf16 v[20:23], v[170:173], v[206:209], v[20:23]
	v_mfma_f32_16x16x32_bf16 v[16:19], v[178:181], v[206:209], v[16:19]
	v_mfma_f32_16x16x32_bf16 v[4:7], v[170:173], v[214:217], v[4:7]
	v_mfma_f32_16x16x32_bf16 v[0:3], v[178:181], v[214:217], v[0:3]
	s_setprio 0
	s_barrier
	s_add_i32 s50, s50, 2
	s_add_u32 s24, s24, 0x100
	s_addc_u32 s25, s25, 0
	s_add_u32 s48, s48, 0x100
	s_addc_u32 s49, s49, 0
	s_cmp_gt_u32 s50, 13
	s_cbranch_scc0 .LBB0_293
	s_branch .Lrw0_x

; __device__ __forceinline__ unsigned cvt_pk_bf16(float lo, float hi) { unsigned r; asm volatile("v_cvt_pk_bf16_f32 %0, %1, %2" : "=v"(r) : "v"(lo), "v"(hi)); return r; }
;     __device__ __forceinline__ void operator()(const f32x4 (&acc)[2][2][4][2], const Unit& u, int wr, int wc, int fr, int fq) const {
;     ...
;                 for (int n = 0; n < 2; ++n)
; #pragma unroll
;                     for (int i = 0; i < 4; ++i) { const float g = acc[ai][0][m][n][i] * rsc, uu = acc[ai][1][m][n][i] * rsc; h[4 * n + i] = g * __builtin_amdgcn_rcpf(1.0f + __builtin_amdgcn_exp2f(g)) * uu; }
;                 u32x4 w; w.x = cvt_pk_bf16(h[0], h[1]); w.y = cvt_pk_bf16(h[2], h[3]); w.z = cvt_pk_bf16(h[4], h[5]); w.w = cvt_pk_bf16(h[6], h[7]);
.Lfz1_tail:
	v_mov_b32_e32 v242, 1.0
	v_exp_f32_e32 v226, v124
	v_exp_f32_e32 v227, v125
	v_exp_f32_e32 v228, v126
	v_exp_f32_e32 v229, v127
	v_exp_f32_e32 v230, v120
	v_exp_f32_e32 v231, v121
	v_exp_f32_e32 v232, v122
	v_exp_f32_e32 v233, v123
	v_exp_f32_e32 v234, v108
	v_exp_f32_e32 v235, v109
	v_exp_f32_e32 v236, v110
	v_exp_f32_e32 v237, v111
	v_exp_f32_e32 v238, v104
	v_exp_f32_e32 v239, v105
	v_exp_f32_e32 v240, v106
	v_exp_f32_e32 v241, v107
	v_pk_add_f32 v[226:227], v[226:227], v[242:243] op_sel_hi:[1,0]
	v_pk_add_f32 v[228:229], v[228:229], v[242:243] op_sel_hi:[1,0]
	v_pk_add_f32 v[230:231], v[230:231], v[242:243] op_sel_hi:[1,0]
	v_pk_add_f32 v[232:233], v[232:233], v[242:243] op_sel_hi:[1,0]
	v_pk_add_f32 v[234:235], v[234:235], v[242:243] op_sel_hi:[1,0]
	v_pk_add_f32 v[236:237], v[236:237], v[242:243] op_sel_hi:[1,0]
	v_pk_add_f32 v[238:239], v[238:239], v[242:243] op_sel_hi:[1,0]
	v_pk_add_f32 v[240:241], v[240:241], v[242:243] op_sel_hi:[1,0]
	v_rcp_f32_e32 v226, v226
	v_rcp_f32_e32 v227, v227
	v_rcp_f32_e32 v228, v228
	v_rcp_f32_e32 v229, v229
	v_rcp_f32_e32 v230, v230
	v_rcp_f32_e32 v231, v231
	v_rcp_f32_e32 v232, v232
	v_rcp_f32_e32 v233, v233
	v_rcp_f32_e32 v234, v234
	v_rcp_f32_e32 v235, v235
	v_rcp_f32_e32 v236, v236
	v_rcp_f32_e32 v237, v237
	v_rcp_f32_e32 v238, v238
	v_rcp_f32_e32 v239, v239
	v_rcp_f32_e32 v240, v240
	v_rcp_f32_e32 v241, v241
	v_pk_mul_f32 v[124:125], v[124:125], v[226:227]
	v_pk_mul_f32 v[126:127], v[126:127], v[228:229]
	v_pk_mul_f32 v[120:121], v[120:121], v[230:231]
	v_pk_mul_f32 v[122:123], v[122:123], v[232:233]
	v_pk_mul_f32 v[108:109], v[108:109], v[234:235]
	v_pk_mul_f32 v[110:111], v[110:111], v[236:237]
	v_pk_mul_f32 v[104:105], v[104:105], v[238:239]
	v_pk_mul_f32 v[106:107], v[106:107], v[240:241]
	v_pk_mul_f32 v[116:117], v[124:125], v[116:117]
	v_pk_mul_f32 v[118:119], v[126:127], v[118:119]
	v_pk_mul_f32 v[112:113], v[120:121], v[112:113]
	v_pk_mul_f32 v[114:115], v[122:123], v[114:115]
	v_pk_mul_f32 v[100:101], v[108:109], v[100:101]
	v_pk_mul_f32 v[102:103], v[110:111], v[102:103]
	v_pk_mul_f32 v[96:97], v[104:105], v[96:97]
	v_pk_mul_f32 v[98:99], v[106:107], v[98:99]
	v_cvt_pk_bf16_f32 v120, v116, v117
	v_cvt_pk_bf16_f32 v121, v118, v119
	v_cvt_pk_bf16_f32 v122, v112, v113
	v_cvt_pk_bf16_f32 v123, v114, v115
	v_cvt_pk_bf16_f32 v104, v100, v101
	v_cvt_pk_bf16_f32 v105, v102, v103
	v_cvt_pk_bf16_f32 v106, v96, v97
	v_cvt_pk_bf16_f32 v107, v98, v99
	s_branch .Lfz1_back
